# GEMM tile order for L2 locality: per-XCD supertile sequence sweeps column supertiles for a fixed row supertile in all four GEMM phases (A panel shared by the two concurrent supertiles, weights/A stay
# speedup vs baseline: 1.0091x; 1.0056x over previous
.LBB0_282:
	s_lshr_b32 s6, s18, 5
	s_mul_i32 s27, s6, 0x1112
	s_lshr_b32 s27, s27, 16
	s_mul_i32 s7, s27, 15
	s_sub_i32 s7, s6, s7
	s_lshl_b32 s6, s27, 3
	s_or_b32 s6, s6, s97
	s_mov_b32 s26, s6
	s_mov_b32 s27, s7
	s_lshl_b32 s7, s18, 7
	s_lshl_b32 s6, s6, 10
	s_and_b32 s7, s7, 0x380
	s_or_b32 s8, s6, s7
	s_lshl_b32 s6, s18, 4
	s_lshl_b32 s14, s27, 9
	s_and_b32 s6, s6, 0x180
	s_or_b32 s6, s14, s6
	s_ashr_i32 s9, s8, 31
	s_ashr_i32 s7, s6, 31
	s_lshl_b64 s[12:13], s[8:9], 10
	s_lshl_b64 s[16:17], s[6:7], 10
	v_readfirstlane_b32 s7, v199
	v_lshl_add_u64 v[0:1], v[152:153], 0, s[12:13]
	v_lshl_add_u64 v[2:3], v[154:155], 0, s[16:17]
	s_mov_b32 m0, s7
	v_readfirstlane_b32 s7, v200
	s_barrier
	global_load_lds_dwordx4 v[0:1], off
	v_lshl_add_u64 v[4:5], v[2:3], 0, v[144:145]
	s_mov_b32 m0, s7
	s_mov_b64 s[12:13], 0x2000
	v_readfirstlane_b32 s7, v201
	global_load_lds_dwordx4 v[4:5], off
	v_lshl_add_u64 v[4:5], v[0:1], 0, s[12:13]
	s_mov_b32 m0, s7
	v_readfirstlane_b32 s7, v202
	global_load_lds_dwordx4 v[4:5], off
	v_lshl_add_u64 v[4:5], v[2:3], 0, v[146:147]
	s_mov_b32 m0, s7
	s_mov_b64 s[12:13], 0x4000
	v_readfirstlane_b32 s7, v203
	global_load_lds_dwordx4 v[4:5], off
	v_lshl_add_u64 v[4:5], v[0:1], 0, s[12:13]
	s_mov_b32 m0, s7
	v_readfirstlane_b32 s7, v204
	global_load_lds_dwordx4 v[4:5], off
	v_lshl_add_u64 v[4:5], v[2:3], 0, v[148:149]
	s_mov_b32 m0, s7
	s_mov_b64 s[12:13], 0x6000
	v_readfirstlane_b32 s7, v205
	global_load_lds_dwordx4 v[4:5], off
	v_lshl_add_u64 v[0:1], v[0:1], 0, s[12:13]
	s_mov_b32 m0, s7
	v_readfirstlane_b32 s7, v206
	global_load_lds_dwordx4 v[0:1], off
	v_lshl_add_u64 v[0:1], v[2:3], 0, v[150:151]
	s_mov_b32 m0, s7
	s_and_b32 s15, s19, 0x180
	global_load_lds_dwordx4 v[0:1], off
	s_or_b32 s12, s14, s15
	s_and_b32 s25, s21, 0x380
	s_ashr_i32 s13, s12, 31
	s_lshl_b32 s7, s26, 10
	s_lshl_b64 s[12:13], s[12:13], 10
	s_or_b32 s7, s7, s25
	s_mov_b32 s9, 0
	v_lshl_add_u64 v[160:161], v[156:157], 0, s[12:13]
	v_lshl_add_u64 v[162:163], v[158:159], 0, s[12:13]
	s_sub_i32 s12, s7, s9
	s_ashr_i32 s13, s12, 31
	s_lshl_b64 s[12:13], s[12:13], 10
	v_lshl_add_u64 v[164:165], v[152:153], 0, s[12:13]
	s_mov_b64 s[12:13], 0
	v_mov_b32_e32 v64, 0
	v_mov_b32_e32 v65, v143
	v_mov_b32_e32 v66, v143
	v_mov_b32_e32 v67, v143
	v_mov_b32_e32 v68, 0
	v_mov_b32_e32 v69, v143
	v_mov_b32_e32 v70, v143
	v_mov_b32_e32 v71, v143
	v_mov_b32_e32 v72, 0
	v_mov_b32_e32 v73, v143
	v_mov_b32_e32 v74, v143
	v_mov_b32_e32 v75, v143
	v_mov_b32_e32 v76, 0
	v_mov_b32_e32 v77, v143
	v_mov_b32_e32 v78, v143
	v_mov_b32_e32 v79, v143
	v_mov_b32_e32 v80, 0
	v_mov_b32_e32 v81, v143
	v_mov_b32_e32 v82, v143
	v_mov_b32_e32 v83, v143
	v_mov_b32_e32 v84, 0
	v_mov_b32_e32 v85, v143
	v_mov_b32_e32 v86, v143
	v_mov_b32_e32 v87, v143
	v_mov_b32_e32 v88, 0
	v_mov_b32_e32 v89, v143
	v_mov_b32_e32 v90, v143
	v_mov_b32_e32 v91, v143
	v_mov_b32_e32 v92, 0
	v_mov_b32_e32 v93, v143
	v_mov_b32_e32 v94, v143
	v_mov_b32_e32 v95, v143
	v_mov_b32_e32 v96, 0
	v_mov_b32_e32 v97, v143
	v_mov_b32_e32 v98, v143
	v_mov_b32_e32 v99, v143
	v_mov_b32_e32 v100, 0
	v_mov_b32_e32 v101, v143
	v_mov_b32_e32 v102, v143
	v_mov_b32_e32 v103, v143
	v_mov_b32_e32 v104, 0
	v_mov_b32_e32 v105, v143
	v_mov_b32_e32 v106, v143
	v_mov_b32_e32 v107, v143
	v_mov_b32_e32 v108, 0
	v_mov_b32_e32 v109, v143
	v_mov_b32_e32 v110, v143
	v_mov_b32_e32 v111, v143
	v_mov_b32_e32 v112, 0
	v_mov_b32_e32 v113, v143
	v_mov_b32_e32 v114, v143
	v_mov_b32_e32 v115, v143
	v_mov_b32_e32 v116, 0
	v_mov_b32_e32 v117, v143
	v_mov_b32_e32 v118, v143
	v_mov_b32_e32 v119, v143
	v_mov_b32_e32 v120, 0
	v_mov_b32_e32 v121, v143
	v_mov_b32_e32 v122, v143
	v_mov_b32_e32 v123, v143
	v_mov_b32_e32 v124, 0
	v_mov_b32_e32 v125, v143
	v_mov_b32_e32 v126, v143
	v_mov_b32_e32 v127, v143
	s_waitcnt vmcnt(0) lgkmcnt(0)
	s_barrier
	s_branch .LBB0_284

.LBB0_703:
	s_lshr_b32 s30, s33, 5
	s_and_b32 s46, s30, 1
	s_lshr_b32 s30, s30, 1
	s_lshl_b32 s30, s30, 3
	s_or_b32 s30, s30, s97
	s_mov_b32 s45, s30
	s_lshl_b32 s31, s33, 7
	s_lshl_b32 s30, s30, 10
	s_and_b32 s31, s31, 0x380
	s_or_b32 s30, s30, s31
	s_lshl_b32 s31, s33, 4
	s_lshl_b32 s47, s46, 9
	s_and_b32 s31, s31, 0x180
	s_or_b32 s34, s47, s31
	s_ashr_i32 s31, s30, 31
	s_lshl_b64 s[36:37], s[30:31], 11
	s_ashr_i32 s35, s34, 31
	s_lshl_b64 s[38:39], s[34:35], 11
	v_lshl_add_u64 v[0:1], v[106:107], 0, s[36:37]
	v_readfirstlane_b32 s36, v169
	v_lshl_add_u64 v[2:3], v[108:109], 0, s[38:39]
	s_mov_b32 m0, s36
	v_readfirstlane_b32 s36, v170
	s_barrier
	global_load_lds_dwordx4 v[0:1], off
	v_lshl_add_u64 v[4:5], v[2:3], 0, v[88:89]
	s_mov_b32 m0, s36
	s_mov_b64 s[36:37], 0x4000
	global_load_lds_dwordx4 v[4:5], off
	v_lshl_add_u64 v[4:5], v[0:1], 0, s[36:37]
	v_readfirstlane_b32 s36, v171
	s_mov_b32 m0, s36
	v_readfirstlane_b32 s36, v177
	global_load_lds_dwordx4 v[4:5], off
	v_lshl_add_u64 v[4:5], v[2:3], 0, v[90:91]
	s_mov_b32 m0, s36
	s_mov_b64 s[36:37], 0x8000
	global_load_lds_dwordx4 v[4:5], off
	v_lshl_add_u64 v[4:5], v[0:1], 0, s[36:37]
	v_readfirstlane_b32 s36, v178
	s_mov_b32 m0, s36
	v_readfirstlane_b32 s36, v179
	global_load_lds_dwordx4 v[4:5], off
	s_mov_b32 m0, s36
	s_mov_b64 s[36:37], 0xc000
	v_lshl_add_u64 v[4:5], v[2:3], 0, v[92:93]
	v_lshl_add_u64 v[0:1], v[0:1], 0, s[36:37]
	v_readfirstlane_b32 s36, v180
	global_load_lds_dwordx4 v[4:5], off
	s_mov_b32 m0, s36
	v_readfirstlane_b32 s36, v181
	global_load_lds_dwordx4 v[0:1], off
	v_lshl_add_u64 v[0:1], v[2:3], 0, v[94:95]
	s_mov_b32 m0, s36
	s_and_b32 s24, s40, 0x180
	global_load_lds_dwordx4 v[0:1], off
	s_or_b32 s36, s47, s24
	s_ashr_i32 s37, s36, 31
	s_and_b32 s44, s42, 0x380
	s_lshl_b64 s[36:37], s[36:37], 11
	s_lshl_b32 s24, s45, 10
	v_lshl_add_u64 v[64:65], v[110:111], 0, s[36:37]
	v_lshl_add_u64 v[66:67], v[112:113], 0, s[36:37]
	s_or_b32 s24, s24, s44
	s_mov_b32 s36, 0
	s_sub_i32 s36, s24, s36
	s_ashr_i32 s37, s36, 31
	s_lshl_b64 s[36:37], s[36:37], 11
	v_lshl_add_u64 v[68:69], v[106:107], 0, s[36:37]
	s_mov_b64 s[36:37], 0
	s_mov_b32 s24, s25
	v_mov_b32_e32 v8, v87
	v_mov_b32_e32 v9, v87
	v_mov_b32_e32 v10, v87
	v_mov_b32_e32 v11, v87
	v_mov_b32_e32 v12, v87
	v_mov_b32_e32 v13, v87
	v_mov_b32_e32 v14, v87
	v_mov_b32_e32 v15, v87
	v_mov_b32_e32 v0, v87
	v_mov_b32_e32 v1, v87
	v_mov_b32_e32 v2, v87
	v_mov_b32_e32 v3, v87
	v_mov_b32_e32 v4, v87
	v_mov_b32_e32 v5, v87
	v_mov_b32_e32 v6, v87
	v_mov_b32_e32 v7, v87
	v_mov_b32_e32 v16, v87
	v_mov_b32_e32 v17, v87
	v_mov_b32_e32 v18, v87
	v_mov_b32_e32 v19, v87
	v_mov_b32_e32 v20, v87
	v_mov_b32_e32 v21, v87
	v_mov_b32_e32 v22, v87
	v_mov_b32_e32 v23, v87
	v_mov_b32_e32 v24, v87
	v_mov_b32_e32 v25, v87
	v_mov_b32_e32 v26, v87
	v_mov_b32_e32 v27, v87
	v_mov_b32_e32 v28, v87
	v_mov_b32_e32 v29, v87
	v_mov_b32_e32 v30, v87
	v_mov_b32_e32 v31, v87
	v_mov_b32_e32 v32, v87
	v_mov_b32_e32 v33, v87
	v_mov_b32_e32 v34, v87
	v_mov_b32_e32 v35, v87
	v_mov_b32_e32 v36, v87
	v_mov_b32_e32 v37, v87
	v_mov_b32_e32 v38, v87
	v_mov_b32_e32 v39, v87
	v_mov_b32_e32 v40, v87
	v_mov_b32_e32 v41, v87
	v_mov_b32_e32 v42, v87
	v_mov_b32_e32 v43, v87
	v_mov_b32_e32 v44, v87
	v_mov_b32_e32 v45, v87
	v_mov_b32_e32 v46, v87
	v_mov_b32_e32 v47, v87
	v_mov_b32_e32 v48, v87
	v_mov_b32_e32 v49, v87
	v_mov_b32_e32 v50, v87
	v_mov_b32_e32 v51, v87
	v_mov_b32_e32 v52, v87
	v_mov_b32_e32 v53, v87
	v_mov_b32_e32 v54, v87
	v_mov_b32_e32 v55, v87
	v_mov_b32_e32 v56, v87
	v_mov_b32_e32 v57, v87
	v_mov_b32_e32 v58, v87
	v_mov_b32_e32 v59, v87
	v_mov_b32_e32 v60, v87
	v_mov_b32_e32 v61, v87
	v_mov_b32_e32 v62, v87
	v_mov_b32_e32 v63, v87
	s_waitcnt vmcnt(0) lgkmcnt(0)
	s_barrier
	s_branch .LBB0_705

.LBB0_768:
	s_lshr_b32 s30, s33, 5
	s_and_b32 s48, s30, 1
	s_lshr_b32 s30, s30, 1
	s_lshl_b32 s30, s30, 3
	s_or_b32 s30, s30, s97
	s_mov_b32 s47, s30
	s_lshl_b32 s31, s33, 7
	s_lshl_b32 s30, s30, 10
	s_and_b32 s31, s31, 0x380
	s_or_b32 s30, s30, s31
	s_lshl_b32 s31, s33, 4
	s_lshl_b32 s49, s48, 9
	s_and_b32 s31, s31, 0x180
	s_or_b32 s34, s49, s31
	s_ashr_i32 s31, s30, 31
	s_ashr_i32 s35, s34, 31
	s_lshl_b64 s[36:37], s[30:31], 11
	s_lshl_b64 s[38:39], s[34:35], 11
	v_readfirstlane_b32 s31, v112
	v_lshl_add_u64 v[0:1], v[86:87], 0, s[36:37]
	v_lshl_add_u64 v[2:3], v[88:89], 0, s[38:39]
	s_mov_b32 m0, s31
	v_readfirstlane_b32 s31, v113
	s_barrier
	global_load_lds_dwordx4 v[0:1], off
	v_lshl_add_u64 v[4:5], v[2:3], 0, v[64:65]
	s_mov_b32 m0, s31
	v_readfirstlane_b32 s31, v114
	global_load_lds_dwordx4 v[4:5], off
	v_lshl_add_u64 v[4:5], v[0:1], 0, s[0:1]
	s_mov_b32 m0, s31
	v_readfirstlane_b32 s31, v115
	global_load_lds_dwordx4 v[4:5], off
	v_lshl_add_u64 v[4:5], v[2:3], 0, v[66:67]
	s_mov_b32 m0, s31
	v_readfirstlane_b32 s31, v116
	global_load_lds_dwordx4 v[4:5], off
	v_lshl_add_u64 v[4:5], v[0:1], 0, s[2:3]
	s_mov_b32 m0, s31
	v_readfirstlane_b32 s31, v117
	global_load_lds_dwordx4 v[4:5], off
	v_lshl_add_u64 v[4:5], v[2:3], 0, v[68:69]
	s_mov_b32 m0, s31
	v_readfirstlane_b32 s31, v118
	global_load_lds_dwordx4 v[4:5], off
	v_lshl_add_u64 v[0:1], v[0:1], 0, s[4:5]
	s_mov_b32 m0, s31
	v_readfirstlane_b32 s31, v119
	global_load_lds_dwordx4 v[0:1], off
	v_lshl_add_u64 v[0:1], v[2:3], 0, v[70:71]
	s_mov_b32 m0, s31
	s_and_b32 s45, s41, 0x180
	global_load_lds_dwordx4 v[0:1], off
	s_or_b32 s36, s49, s45
	s_and_b32 s46, s43, 0x380
	s_ashr_i32 s37, s36, 31
	s_lshl_b32 s31, s47, 10
	s_lshl_b64 s[36:37], s[36:37], 11
	s_or_b32 s31, s31, s46
	s_mov_b32 s35, 0
	s_waitcnt vmcnt(0)
	v_lshl_add_u64 v[94:95], v[90:91], 0, s[36:37]
	v_lshl_add_u64 v[96:97], v[92:93], 0, s[36:37]
	s_sub_i32 s36, s31, s35
	s_ashr_i32 s37, s36, 31
	s_lshl_b64 s[36:37], s[36:37], 11
	v_lshl_add_u64 v[98:99], v[86:87], 0, s[36:37]
	s_mov_b64 s[36:37], 0
	s_mov_b32 s31, 0
	v_mov_b32_e32 v8, 0
	v_mov_b32_e32 v9, v65
	v_mov_b32_e32 v10, v65
	v_mov_b32_e32 v11, v65
	v_mov_b32_e32 v16, 0
	v_mov_b32_e32 v17, v65
	v_mov_b32_e32 v18, v65
	v_mov_b32_e32 v19, v65
	v_mov_b32_e32 v0, 0
	v_mov_b32_e32 v1, v65
	v_mov_b32_e32 v2, v65
	v_mov_b32_e32 v3, v65
	v_mov_b32_e32 v4, 0
	v_mov_b32_e32 v5, v65
	v_mov_b32_e32 v6, v65
	v_mov_b32_e32 v7, v65
	v_mov_b32_e32 v12, 0
	v_mov_b32_e32 v13, v65
	v_mov_b32_e32 v14, v65
	v_mov_b32_e32 v15, v65
	v_mov_b32_e32 v20, 0
	v_mov_b32_e32 v21, v65
	v_mov_b32_e32 v22, v65
	v_mov_b32_e32 v23, v65
	v_mov_b32_e32 v24, 0
	v_mov_b32_e32 v25, v65
	v_mov_b32_e32 v26, v65
	v_mov_b32_e32 v27, v65
	v_mov_b32_e32 v28, 0
	v_mov_b32_e32 v29, v65
	v_mov_b32_e32 v30, v65
	v_mov_b32_e32 v31, v65
	v_mov_b32_e32 v32, 0
	v_mov_b32_e32 v33, v65
	v_mov_b32_e32 v34, v65
	v_mov_b32_e32 v35, v65
	v_mov_b32_e32 v36, 0
	v_mov_b32_e32 v37, v65
	v_mov_b32_e32 v38, v65
	v_mov_b32_e32 v39, v65
	v_mov_b32_e32 v40, 0
	v_mov_b32_e32 v41, v65
	v_mov_b32_e32 v42, v65
	v_mov_b32_e32 v43, v65
	v_mov_b32_e32 v44, 0
	v_mov_b32_e32 v45, v65
	v_mov_b32_e32 v46, v65
	v_mov_b32_e32 v47, v65
	v_mov_b32_e32 v48, 0
	v_mov_b32_e32 v49, v65
	v_mov_b32_e32 v50, v65
	v_mov_b32_e32 v51, v65
	v_mov_b32_e32 v52, 0
	v_mov_b32_e32 v53, v65
	v_mov_b32_e32 v54, v65
	v_mov_b32_e32 v55, v65
	v_mov_b32_e32 v56, 0
	v_mov_b32_e32 v57, v65
	v_mov_b32_e32 v58, v65
	v_mov_b32_e32 v59, v65
	v_mov_b32_e32 v60, 0
	v_mov_b32_e32 v61, v65
	v_mov_b32_e32 v62, v65
	v_mov_b32_e32 v63, v65
	s_waitcnt lgkmcnt(0)
	s_barrier
	s_branch .LBB0_770

.LBB0_886:
	s_lshr_b32 s26, s33, 5
	s_and_b32 s43, s26, 3
	s_lshr_b32 s26, s26, 2
	s_lshl_b32 s26, s26, 3
	s_or_b32 s26, s26, s97
	s_mov_b32 s42, s26
	s_lshl_b32 s27, s33, 7
	s_lshl_b32 s26, s26, 10
	s_and_b32 s27, s27, 0x380
	s_or_b32 s26, s26, s27
	s_lshl_b32 s27, s33, 4
	s_lshl_b32 s44, s43, 9
	s_and_b32 s27, s27, 0x180
	s_or_b32 s28, s44, s27
	s_ashr_i32 s27, s26, 31
	s_ashr_i32 s29, s28, 31
	s_lshl_b64 s[30:31], s[26:27], 11
	s_lshl_b64 s[34:35], s[28:29], 11
	v_readfirstlane_b32 s27, v73
	v_lshl_add_u64 v[0:1], v[86:87], 0, s[30:31]
	v_lshl_add_u64 v[2:3], v[88:89], 0, s[34:35]
	s_mov_b32 m0, s27
	v_readfirstlane_b32 s27, v77
	s_barrier
	global_load_lds_dwordx4 v[0:1], off
	v_lshl_add_u64 v[4:5], v[2:3], 0, v[64:65]
	s_mov_b32 m0, s27
	v_readfirstlane_b32 s27, v111
	global_load_lds_dwordx4 v[4:5], off
	v_lshl_add_u64 v[4:5], v[0:1], 0, s[0:1]
	s_mov_b32 m0, s27
	v_readfirstlane_b32 s27, v112
	global_load_lds_dwordx4 v[4:5], off
	v_lshl_add_u64 v[4:5], v[2:3], 0, v[66:67]
	s_mov_b32 m0, s27
	v_readfirstlane_b32 s27, v113
	global_load_lds_dwordx4 v[4:5], off
	v_lshl_add_u64 v[4:5], v[0:1], 0, s[2:3]
	s_mov_b32 m0, s27
	v_readfirstlane_b32 s27, v114
	global_load_lds_dwordx4 v[4:5], off
	v_lshl_add_u64 v[4:5], v[2:3], 0, v[68:69]
	s_mov_b32 m0, s27
	v_readfirstlane_b32 s27, v115
	global_load_lds_dwordx4 v[4:5], off
	v_lshl_add_u64 v[0:1], v[0:1], 0, s[4:5]
	s_mov_b32 m0, s27
	v_readfirstlane_b32 s27, v116
	global_load_lds_dwordx4 v[0:1], off
	v_lshl_add_u64 v[0:1], v[2:3], 0, v[70:71]
	s_mov_b32 m0, s27
	s_and_b32 s40, s36, 0x180
	global_load_lds_dwordx4 v[0:1], off
	s_or_b32 s30, s44, s40
	s_and_b32 s41, s38, 0x380
	s_ashr_i32 s31, s30, 31
	s_lshl_b32 s27, s42, 10
	s_lshl_b64 s[30:31], s[30:31], 11
	s_or_b32 s27, s27, s41
	s_mov_b32 s29, 0
	v_lshl_add_u64 v[94:95], v[90:91], 0, s[30:31]
	v_lshl_add_u64 v[96:97], v[92:93], 0, s[30:31]
	s_sub_i32 s30, s27, s29
	s_ashr_i32 s31, s30, 31
	s_lshl_b64 s[30:31], s[30:31], 11
	v_lshl_add_u64 v[98:99], v[86:87], 0, s[30:31]
	s_mov_b32 s27, 0
	s_mov_b64 s[30:31], 0
	v_mov_b32_e32 v24, 0
	v_mov_b32_e32 v25, v65
	v_mov_b32_e32 v26, v65
	v_mov_b32_e32 v27, v65
	v_mov_b32_e32 v28, 0
	v_mov_b32_e32 v29, v65
	v_mov_b32_e32 v30, v65
	v_mov_b32_e32 v31, v65
	v_mov_b32_e32 v0, 0
	v_mov_b32_e32 v1, v65
	v_mov_b32_e32 v2, v65
	v_mov_b32_e32 v3, v65
	v_mov_b32_e32 v4, 0
	v_mov_b32_e32 v5, v65
	v_mov_b32_e32 v6, v65
	v_mov_b32_e32 v7, v65
	v_mov_b32_e32 v8, 0
	v_mov_b32_e32 v9, v65
	v_mov_b32_e32 v10, v65
	v_mov_b32_e32 v11, v65
	v_mov_b32_e32 v12, 0
	v_mov_b32_e32 v13, v65
	v_mov_b32_e32 v14, v65
	v_mov_b32_e32 v15, v65
	v_mov_b32_e32 v16, 0
	v_mov_b32_e32 v17, v65
	v_mov_b32_e32 v18, v65
	v_mov_b32_e32 v19, v65
	v_mov_b32_e32 v20, 0
	v_mov_b32_e32 v21, v65
	v_mov_b32_e32 v22, v65
	v_mov_b32_e32 v23, v65
	v_mov_b32_e32 v32, 0
	v_mov_b32_e32 v33, v65
	v_mov_b32_e32 v34, v65
	v_mov_b32_e32 v35, v65
	v_mov_b32_e32 v36, 0
	v_mov_b32_e32 v37, v65
	v_mov_b32_e32 v38, v65
	v_mov_b32_e32 v39, v65
	v_mov_b32_e32 v40, 0
	v_mov_b32_e32 v41, v65
	v_mov_b32_e32 v42, v65
	v_mov_b32_e32 v43, v65
	v_mov_b32_e32 v44, 0
	v_mov_b32_e32 v45, v65
	v_mov_b32_e32 v46, v65
	v_mov_b32_e32 v47, v65
	v_mov_b32_e32 v48, 0
	v_mov_b32_e32 v49, v65
	v_mov_b32_e32 v50, v65
	v_mov_b32_e32 v51, v65
	v_mov_b32_e32 v52, 0
	v_mov_b32_e32 v53, v65
	v_mov_b32_e32 v54, v65
	v_mov_b32_e32 v55, v65
	v_mov_b32_e32 v56, 0
	v_mov_b32_e32 v57, v65
	v_mov_b32_e32 v58, v65
	v_mov_b32_e32 v59, v65
	v_mov_b32_e32 v60, 0
	v_mov_b32_e32 v61, v65
	v_mov_b32_e32 v62, v65
	v_mov_b32_e32 v63, v65
	s_waitcnt vmcnt(0) lgkmcnt(0)
	s_barrier
	s_branch .LBB0_888
